# MT0 masked tiles: dead v_mov zero-inits removed after unconditional bias reads; MT1 with scheduler-interleaved QK
# speedup vs baseline: 1.0135x; 1.0002x over previous
.LBB0_735:
	s_add_i32 s8, s6, -1
	s_min_i32 s9, s6, 35
	s_cmp_lt_u32 s8, 31
	s_cselect_b32 s15, 0, 0xffffffe0
	s_cselect_b32 s16, s13, s14
	s_add_i32 s15, s15, s9
	s_lshl_b32 s9, s15, 6
	s_add_i32 s9, s9, s16
	s_and_b32 s16, s8, 1
	s_mul_i32 s15, s16, 0x3400
	s_mulk_i32 s16, 0x3000
	v_add_u32_e32 v244, s15, v184
	v_add_u32_e32 v246, s16, v243
	ds_read_b128 v[218:221], v244
	ds_read_b128 v[222:225], v244 offset:6656
	ds_read_b128 v[226:229], v244 offset:32
	ds_read_b128 v[230:233], v244 offset:6688
	ds_read_b128 v[168:171], v244 offset:64
	ds_read_b128 v[172:175], v244 offset:6720
	ds_read_b128 v[176:179], v244 offset:96
	ds_read_b128 v[180:183], v244 offset:6752
	s_waitcnt lgkmcnt(7)
	v_mfma_f32_32x32x16_bf16 v[96:111], v[218:221], v[128:131], v[48:63]
	s_waitcnt lgkmcnt(6)
	v_mfma_f32_32x32x16_bf16 v[112:127], v[222:225], v[128:131], v[48:63]
	s_waitcnt lgkmcnt(5)
	v_mfma_f32_32x32x16_bf16 v[96:111], v[226:229], v[132:135], v[96:111]
	s_waitcnt lgkmcnt(4)
	v_mfma_f32_32x32x16_bf16 v[112:127], v[230:233], v[132:135], v[112:127]
	ds_read_b64_tr_b16 v[152:153], v246 offset:26624
	ds_read_b64_tr_b16 v[154:155], v246 offset:28160
	ds_read_b64_tr_b16 v[156:157], v246 offset:26688
	ds_read_b64_tr_b16 v[158:159], v246 offset:28224
	ds_read_b64_tr_b16 v[160:161], v246 offset:29696
	ds_read_b64_tr_b16 v[162:163], v246 offset:31232
	ds_read_b64_tr_b16 v[164:165], v246 offset:29760
	ds_read_b64_tr_b16 v[166:167], v246 offset:31296
	v_add_u32_e32 v186, s9, v239
	v_mad_i64_i32 v[186:187], s[16:17], v186, s33, v[194:195]
	v_add_u32_e32 v188, s9, v240
	v_mad_i64_i32 v[188:189], s[16:17], v188, s33, v[196:197]
	global_load_dwordx4 v[148:151], v[186:187], off
	global_load_dwordx4 v[144:147], v[188:189], off
	s_waitcnt lgkmcnt(11)
	v_mfma_f32_32x32x16_bf16 v[202:217], v[168:171], v[136:139], v[80:95]
	v_exp_f32_e32 v96, v96
	v_exp_f32_e32 v97, v97
	v_exp_f32_e32 v98, v98
	s_waitcnt lgkmcnt(10)
	v_mfma_f32_32x32x16_bf16 v[218:233], v[172:175], v[136:139], v[80:95]
	v_exp_f32_e32 v99, v99
	v_exp_f32_e32 v100, v100
	v_exp_f32_e32 v101, v101
	s_waitcnt lgkmcnt(9)
	v_mfma_f32_32x32x16_bf16 v[202:217], v[176:179], v[140:143], v[202:217]
	v_exp_f32_e32 v102, v102
	v_exp_f32_e32 v103, v103
	v_add_f32_e32 v234, v96, v98
	v_add_f32_e32 v235, v97, v99
	s_waitcnt lgkmcnt(8)
	v_mfma_f32_32x32x16_bf16 v[218:233], v[180:183], v[140:143], v[218:233]
	v_add_f32_e32 v234, v234, v100
	v_add_f32_e32 v235, v235, v101
	v_add_f32_e32 v234, v234, v102
	v_add_f32_e32 v235, v235, v103
	v_cvt_pk_bf16_f32 v96, v96, v97
	v_cvt_pk_bf16_f32 v97, v98, v99
	s_waitcnt lgkmcnt(7)
	ds_read_b64_tr_b16 v[168:169], v246 offset:32768
	ds_read_b64_tr_b16 v[170:171], v246 offset:34304
	ds_read_b64_tr_b16 v[172:173], v246 offset:32832
	ds_read_b64_tr_b16 v[174:175], v246 offset:34368
	ds_read_b64_tr_b16 v[176:177], v246 offset:35840
	ds_read_b64_tr_b16 v[178:179], v246 offset:37376
	ds_read_b64_tr_b16 v[180:181], v246 offset:35904
	ds_read_b64_tr_b16 v[182:183], v246 offset:37440
	v_cvt_pk_bf16_f32 v98, v100, v101
	v_cvt_pk_bf16_f32 v99, v102, v103
	v_exp_f32_e32 v104, v104
	v_exp_f32_e32 v105, v105
	s_waitcnt lgkmcnt(14)
	v_mfma_f32_32x32x16_bf16 v[16:31], v[152:155], v[96:99], v[16:31]
	v_exp_f32_e32 v106, v106
	v_exp_f32_e32 v107, v107
	v_exp_f32_e32 v108, v108
	s_waitcnt lgkmcnt(12)
	v_mfma_f32_32x32x16_bf16 v[0:15], v[156:159], v[96:99], v[0:15]
	v_exp_f32_e32 v109, v109
	v_exp_f32_e32 v110, v110
	v_exp_f32_e32 v111, v111
	v_add_f32_e32 v234, v234, v104
	v_add_f32_e32 v235, v235, v105
	v_add_f32_e32 v234, v234, v106
	v_add_f32_e32 v235, v235, v107
	v_add_f32_e32 v234, v234, v108
	v_add_f32_e32 v235, v235, v109
	v_add_f32_e32 v234, v234, v110
	v_add_f32_e32 v235, v235, v111
	v_cvt_pk_bf16_f32 v104, v104, v105
	v_cvt_pk_bf16_f32 v105, v106, v107
	v_cvt_pk_bf16_f32 v106, v108, v109
	v_cvt_pk_bf16_f32 v107, v110, v111
	v_exp_f32_e32 v112, v112
	v_exp_f32_e32 v113, v113
	s_waitcnt lgkmcnt(10)
	v_mfma_f32_32x32x16_bf16 v[16:31], v[160:163], v[104:107], v[16:31]
	v_exp_f32_e32 v114, v114
	v_exp_f32_e32 v115, v115
	v_exp_f32_e32 v116, v116
	s_waitcnt lgkmcnt(8)
	v_mfma_f32_32x32x16_bf16 v[0:15], v[164:167], v[104:107], v[0:15]
	v_exp_f32_e32 v117, v117
	v_exp_f32_e32 v118, v118
	v_exp_f32_e32 v119, v119
	v_add_f32_e32 v234, v234, v112
	v_add_f32_e32 v235, v235, v113
	v_add_f32_e32 v234, v234, v114
	v_add_f32_e32 v235, v235, v115
	v_add_f32_e32 v234, v234, v116
	v_add_f32_e32 v235, v235, v117
	v_add_f32_e32 v234, v234, v118
	v_add_f32_e32 v235, v235, v119
	v_cvt_pk_bf16_f32 v112, v112, v113
	v_cvt_pk_bf16_f32 v113, v114, v115
	v_cvt_pk_bf16_f32 v114, v116, v117
	v_cvt_pk_bf16_f32 v115, v118, v119
	v_exp_f32_e32 v120, v120
	v_exp_f32_e32 v121, v121
	s_waitcnt lgkmcnt(6)
	v_mfma_f32_32x32x16_bf16 v[16:31], v[168:171], v[112:115], v[16:31]
	v_exp_f32_e32 v122, v122
	v_exp_f32_e32 v123, v123
	v_exp_f32_e32 v124, v124
	s_waitcnt lgkmcnt(4)
	v_mfma_f32_32x32x16_bf16 v[0:15], v[172:175], v[112:115], v[0:15]
	v_exp_f32_e32 v125, v125
	v_exp_f32_e32 v126, v126
	v_exp_f32_e32 v127, v127
	v_add_f32_e32 v234, v234, v120
	v_add_f32_e32 v235, v235, v121
	v_add_f32_e32 v234, v234, v122
	v_add_f32_e32 v235, v235, v123
	v_add_f32_e32 v234, v234, v124
	v_add_f32_e32 v235, v235, v125
	v_add_f32_e32 v234, v234, v126
	v_add_f32_e32 v235, v235, v127
	v_cvt_pk_bf16_f32 v120, v120, v121
	v_cvt_pk_bf16_f32 v121, v122, v123
	v_cvt_pk_bf16_f32 v122, v124, v125
	v_cvt_pk_bf16_f32 v123, v126, v127
	v_exp_f32_e32 v202, v202
	v_exp_f32_e32 v203, v203
	s_waitcnt lgkmcnt(2)
	v_mfma_f32_32x32x16_bf16 v[16:31], v[176:179], v[120:123], v[16:31]
	v_exp_f32_e32 v204, v204
	v_exp_f32_e32 v205, v205
	v_exp_f32_e32 v206, v206
	s_waitcnt lgkmcnt(0)
	v_mfma_f32_32x32x16_bf16 v[0:15], v[180:183], v[120:123], v[0:15]
	v_exp_f32_e32 v207, v207
	v_exp_f32_e32 v208, v208
	v_exp_f32_e32 v209, v209
	s_cmp_gt_u32 s8, 34
	s_cbranch_scc1 .Lm3_skipw
	s_and_b32 s8, s7, 64
	s_mul_i32 s9, s8, 0xd0
	s_mulk_i32 s8, 0xc0
	v_add_u32_e32 v186, s9, v241
	v_add_u32_e32 v188, s8, v242
	s_waitcnt vmcnt(1)
	ds_write_b128 v186, v[148:151]
	s_waitcnt vmcnt(0)
	ds_write_b128 v188, v[144:147] offset:26624
.Lm3_skipw:
	v_add_f32_e32 v236, v202, v204
	v_add_f32_e32 v237, v203, v205
	v_add_f32_e32 v236, v236, v206
	v_add_f32_e32 v237, v237, v207
	v_add_f32_e32 v236, v236, v208
	v_add_f32_e32 v237, v237, v209
	v_cvt_pk_bf16_f32 v202, v202, v203
	v_cvt_pk_bf16_f32 v203, v204, v205
	v_cvt_pk_bf16_f32 v204, v206, v207
	v_cvt_pk_bf16_f32 v205, v208, v209
	v_exp_f32_e32 v210, v210
	v_exp_f32_e32 v211, v211
	v_mfma_f32_32x32x16_bf16 v[64:79], v[152:155], v[202:205], v[64:79]
	v_exp_f32_e32 v212, v212
	v_exp_f32_e32 v213, v213
	v_exp_f32_e32 v214, v214
	v_mfma_f32_32x32x16_bf16 v[32:47], v[156:159], v[202:205], v[32:47]
	v_exp_f32_e32 v215, v215
	v_exp_f32_e32 v216, v216
	v_exp_f32_e32 v217, v217
	v_add_f32_e32 v236, v236, v210
	v_add_f32_e32 v237, v237, v211
	v_add_f32_e32 v236, v236, v212
	v_add_f32_e32 v237, v237, v213
	v_add_f32_e32 v236, v236, v214
	v_add_f32_e32 v237, v237, v215
	v_add_f32_e32 v236, v236, v216
	v_add_f32_e32 v237, v237, v217
	v_cvt_pk_bf16_f32 v210, v210, v211
	v_cvt_pk_bf16_f32 v211, v212, v213
	v_cvt_pk_bf16_f32 v212, v214, v215
	v_cvt_pk_bf16_f32 v213, v216, v217
	v_exp_f32_e32 v218, v218
	v_exp_f32_e32 v219, v219
	v_mfma_f32_32x32x16_bf16 v[64:79], v[160:163], v[210:213], v[64:79]
	v_exp_f32_e32 v220, v220
	v_exp_f32_e32 v221, v221
	v_exp_f32_e32 v222, v222
	v_mfma_f32_32x32x16_bf16 v[32:47], v[164:167], v[210:213], v[32:47]
	v_exp_f32_e32 v223, v223
	v_exp_f32_e32 v224, v224
	v_exp_f32_e32 v225, v225
	v_add_f32_e32 v236, v236, v218
	v_add_f32_e32 v237, v237, v219
	v_add_f32_e32 v236, v236, v220
	v_add_f32_e32 v237, v237, v221
	v_add_f32_e32 v236, v236, v222
	v_add_f32_e32 v237, v237, v223
	v_add_f32_e32 v236, v236, v224
	v_add_f32_e32 v237, v237, v225
	v_cvt_pk_bf16_f32 v218, v218, v219
	v_cvt_pk_bf16_f32 v219, v220, v221
	v_cvt_pk_bf16_f32 v220, v222, v223
	v_cvt_pk_bf16_f32 v221, v224, v225
	v_exp_f32_e32 v226, v226
	v_exp_f32_e32 v227, v227
	v_mfma_f32_32x32x16_bf16 v[64:79], v[168:171], v[218:221], v[64:79]
	v_exp_f32_e32 v228, v228
	v_exp_f32_e32 v229, v229
	v_exp_f32_e32 v230, v230
	v_mfma_f32_32x32x16_bf16 v[32:47], v[172:175], v[218:221], v[32:47]
	v_exp_f32_e32 v231, v231
	v_exp_f32_e32 v232, v232
	v_exp_f32_e32 v233, v233
	v_add_f32_e32 v236, v236, v226
	v_add_f32_e32 v237, v237, v227
	v_add_f32_e32 v236, v236, v228
	v_add_f32_e32 v237, v237, v229
	v_add_f32_e32 v236, v236, v230
	v_add_f32_e32 v237, v237, v231
	v_add_f32_e32 v236, v236, v232
	v_add_f32_e32 v237, v237, v233
	v_cvt_pk_bf16_f32 v226, v226, v227
	v_cvt_pk_bf16_f32 v227, v228, v229
	v_cvt_pk_bf16_f32 v228, v230, v231
	v_cvt_pk_bf16_f32 v229, v232, v233
	s_nop 1
	v_mfma_f32_32x32x16_bf16 v[64:79], v[176:179], v[226:229], v[64:79]
	v_mfma_f32_32x32x16_bf16 v[32:47], v[180:183], v[226:229], v[32:47]
	v_add_f32_e32 v234, v234, v235
	v_add_f32_e32 v236, v236, v237
	v_add_f32_e32 v199, v199, v234
	v_add_f32_e32 v201, v201, v236
	v_max_f32_e32 v247, v234, v236
	v_cmp_lt_f32_e32 vcc, 0x43000000, v247
	s_cbranch_vccz .Lm3_norescale
	s_nop 15
	v_mov_b32_e32 v235, v234
	s_nop 1
	v_permlane32_swap_b32_e32 v234, v235
	v_add_f32_e32 v247, v234, v235
	v_cmp_lt_f32_e32 vcc, 0x43800000, v247
	v_frexp_exp_i32_f32_e32 v248, v247
	s_nop 1
	v_cndmask_b32_e32 v248, 0, v248, vcc
	v_cvt_f32_i32_e32 v249, v248
	v_sub_u32_e32 v248, 0, v248
	v_ldexp_f32 v247, 1.0, v248
	v_add_f32_e32 v198, v198, v249
	v_mul_f32_e32 v199, v199, v247
	v_mul_f32_e32 v16, v16, v247
	v_mul_f32_e32 v17, v17, v247
	v_mul_f32_e32 v18, v18, v247
	v_mul_f32_e32 v19, v19, v247
	v_mul_f32_e32 v20, v20, v247
	v_mul_f32_e32 v21, v21, v247
	v_mul_f32_e32 v22, v22, v247
	v_mul_f32_e32 v23, v23, v247
	v_mul_f32_e32 v24, v24, v247
	v_mul_f32_e32 v25, v25, v247
	v_mul_f32_e32 v26, v26, v247
	v_mul_f32_e32 v27, v27, v247
	v_mul_f32_e32 v28, v28, v247
	v_mul_f32_e32 v29, v29, v247
	v_mul_f32_e32 v30, v30, v247
	v_mul_f32_e32 v31, v31, v247
	v_mul_f32_e32 v0, v0, v247
	v_mul_f32_e32 v1, v1, v247
	v_mul_f32_e32 v2, v2, v247
	v_mul_f32_e32 v3, v3, v247
	v_mul_f32_e32 v4, v4, v247
	v_mul_f32_e32 v5, v5, v247
	v_mul_f32_e32 v6, v6, v247
	v_mul_f32_e32 v7, v7, v247
	v_mul_f32_e32 v8, v8, v247
	v_mul_f32_e32 v9, v9, v247
	v_mul_f32_e32 v10, v10, v247
	v_mul_f32_e32 v11, v11, v247
	v_mul_f32_e32 v12, v12, v247
	v_mul_f32_e32 v13, v13, v247
	v_mul_f32_e32 v14, v14, v247
	v_mul_f32_e32 v15, v15, v247
	v_sub_f32_e32 v48, 0, v198
	v_mov_b32_e32 v49, v48
	v_mov_b32_e32 v50, v48
	v_mov_b32_e32 v51, v48
	v_mov_b32_e32 v52, v48
	v_mov_b32_e32 v53, v48
	v_mov_b32_e32 v54, v48
	v_mov_b32_e32 v55, v48
	v_mov_b32_e32 v56, v48
	v_mov_b32_e32 v57, v48
	v_mov_b32_e32 v58, v48
	v_mov_b32_e32 v59, v48
	v_mov_b32_e32 v60, v48
	v_mov_b32_e32 v61, v48
	v_mov_b32_e32 v62, v48
	v_mov_b32_e32 v63, v48
	v_mov_b32_e32 v237, v236
	s_nop 1
	v_permlane32_swap_b32_e32 v236, v237
	v_add_f32_e32 v247, v236, v237
	v_cmp_lt_f32_e32 vcc, 0x43800000, v247
	v_frexp_exp_i32_f32_e32 v248, v247
	s_nop 1
	v_cndmask_b32_e32 v248, 0, v248, vcc
	v_cvt_f32_i32_e32 v249, v248
	v_sub_u32_e32 v248, 0, v248
	v_ldexp_f32 v247, 1.0, v248
	v_add_f32_e32 v200, v200, v249
	v_mul_f32_e32 v201, v201, v247
	v_mul_f32_e32 v64, v64, v247
	v_mul_f32_e32 v65, v65, v247
	v_mul_f32_e32 v66, v66, v247
	v_mul_f32_e32 v67, v67, v247
	v_mul_f32_e32 v68, v68, v247
	v_mul_f32_e32 v69, v69, v247
	v_mul_f32_e32 v70, v70, v247
	v_mul_f32_e32 v71, v71, v247
	v_mul_f32_e32 v72, v72, v247
	v_mul_f32_e32 v73, v73, v247
	v_mul_f32_e32 v74, v74, v247
	v_mul_f32_e32 v75, v75, v247
	v_mul_f32_e32 v76, v76, v247
	v_mul_f32_e32 v77, v77, v247
	v_mul_f32_e32 v78, v78, v247
	v_mul_f32_e32 v79, v79, v247
	v_mul_f32_e32 v32, v32, v247
	v_mul_f32_e32 v33, v33, v247
	v_mul_f32_e32 v34, v34, v247
	v_mul_f32_e32 v35, v35, v247
	v_mul_f32_e32 v36, v36, v247
	v_mul_f32_e32 v37, v37, v247
	v_mul_f32_e32 v38, v38, v247
	v_mul_f32_e32 v39, v39, v247
	v_mul_f32_e32 v40, v40, v247
	v_mul_f32_e32 v41, v41, v247
	v_mul_f32_e32 v42, v42, v247
	v_mul_f32_e32 v43, v43, v247
	v_mul_f32_e32 v44, v44, v247
	v_mul_f32_e32 v45, v45, v247
	v_mul_f32_e32 v46, v46, v247
	v_mul_f32_e32 v47, v47, v247
	v_sub_f32_e32 v80, 0, v200
	v_mov_b32_e32 v81, v80
	v_mov_b32_e32 v82, v80
	v_mov_b32_e32 v83, v80
	v_mov_b32_e32 v84, v80
	v_mov_b32_e32 v85, v80
	v_mov_b32_e32 v86, v80
	v_mov_b32_e32 v87, v80
	v_mov_b32_e32 v88, v80
	v_mov_b32_e32 v89, v80
	v_mov_b32_e32 v90, v80
	v_mov_b32_e32 v91, v80
	v_mov_b32_e32 v92, v80
	v_mov_b32_e32 v93, v80
	v_mov_b32_e32 v94, v80
	v_mov_b32_e32 v95, v80

.LBB0_783:
	ds_read_b128 v[48:51], v184 offset:0
	ds_read_b128 v[52:55], v184 offset:32
	ds_read_b128 v[56:59], v184 offset:64
	ds_read_b128 v[60:63], v184 offset:96
	ds_read_b128 v[64:67], v184 offset:128
	ds_read_b128 v[68:71], v184 offset:160
	ds_read_b128 v[72:75], v184 offset:6656
	ds_read_b128 v[76:79], v184 offset:6688
	ds_read_b128 v[80:83], v184 offset:6720
	ds_read_b128 v[84:87], v184 offset:6752
	ds_read_b128 v[88:91], v184 offset:6784
	ds_read_b128 v[92:95], v184 offset:6816
	s_add_i32 s16, s13, 2
	s_min_u32 s6, s16, 35
	s_cmp_lt_u32 s13, 30
	s_cselect_b32 s7, 0, 0xffffffe0
	s_cselect_b32 s8, s15, s12
	s_add_i32 s7, s7, s6
	s_lshl_b32 s6, s7, 6
	s_add_i32 s8, s6, s8
	v_add_u32_e32 v208, s8, v194
	v_ashrrev_i32_e32 v209, 31, v208
	s_and_saveexec_b64 s[6:7], s[0:1]
	s_xor_b64 s[6:7], exec, s[6:7]
	v_mad_i64_i32 v[206:207], s[10:11], v208, s33, v[180:181]
	v_lshl_add_u64 v[206:207], v[206:207], 0, s[28:29]
	s_andn2_saveexec_b64 s[6:7], s[6:7]
	v_lshlrev_b64 v[206:207], 9, v[208:209]
	v_lshl_add_u64 v[206:207], v[182:183], 0, v[206:207]
	s_or_b64 exec, exec, s[6:7]
	global_load_dwordx4 v[132:135], v[206:207], off
	v_or_b32_e32 v208, s8, v195
	v_ashrrev_i32_e32 v209, 31, v208
	s_and_saveexec_b64 s[6:7], s[2:3]
	s_xor_b64 s[6:7], exec, s[6:7]
	v_mad_i64_i32 v[206:207], s[10:11], v208, s33, v[190:191]
	v_lshl_add_u64 v[206:207], v[206:207], 0, s[28:29]
	s_andn2_saveexec_b64 s[6:7], s[6:7]
	v_lshlrev_b64 v[206:207], 9, v[208:209]
	v_lshl_add_u64 v[206:207], v[192:193], 0, v[206:207]
	s_or_b64 exec, exec, s[6:7]
	global_load_dwordx4 v[136:139], v[206:207], off
	v_add_u32_e32 v206, s8, v196
	v_ashrrev_i32_e32 v207, 31, v206
	v_lshlrev_b64 v[206:207], 9, v[206:207]
	v_lshl_add_u64 v[206:207], v[178:179], 0, v[206:207]
	global_load_dwordx4 v[140:143], v[206:207], off
	s_waitcnt lgkmcnt(11)
	v_mfma_f32_32x32x16_bf16 v[144:159], v[48:51], v[96:99], v[32:47]
	s_waitcnt lgkmcnt(10)
	v_mfma_f32_32x32x16_bf16 v[144:159], v[52:55], v[100:103], v[144:159]
	s_waitcnt lgkmcnt(9)
	v_mfma_f32_32x32x16_bf16 v[144:159], v[56:59], v[104:107], v[144:159]
	s_waitcnt lgkmcnt(8)
	v_mfma_f32_32x32x16_bf16 v[144:159], v[60:63], v[108:111], v[144:159]
	s_waitcnt lgkmcnt(7)
	v_mfma_f32_32x32x16_bf16 v[144:159], v[64:67], v[112:115], v[144:159]
	s_waitcnt lgkmcnt(6)
	v_mfma_f32_32x32x16_bf16 v[144:159], v[68:71], v[116:119], v[144:159]
	s_waitcnt lgkmcnt(5)
	v_mfma_f32_32x32x16_bf16 v[160:175], v[72:75], v[96:99], v[32:47]
	s_waitcnt lgkmcnt(4)
	v_mfma_f32_32x32x16_bf16 v[160:175], v[76:79], v[100:103], v[160:175]
	s_waitcnt lgkmcnt(3)
	v_mfma_f32_32x32x16_bf16 v[160:175], v[80:83], v[104:107], v[160:175]
	s_nop 5
	s_waitcnt lgkmcnt(2)
	v_mfma_f32_32x32x16_bf16 v[160:175], v[84:87], v[108:111], v[160:175]
	v_exp_f32_e32 v144, v144
	v_exp_f32_e32 v145, v145
	v_exp_f32_e32 v146, v146
	s_waitcnt lgkmcnt(1)
	v_mfma_f32_32x32x16_bf16 v[160:175], v[88:91], v[112:115], v[160:175]
	v_exp_f32_e32 v147, v147
	v_exp_f32_e32 v148, v148
	v_exp_f32_e32 v149, v149
	s_waitcnt lgkmcnt(0)
	v_mfma_f32_32x32x16_bf16 v[160:175], v[92:95], v[116:119], v[160:175]
	v_exp_f32_e32 v150, v150
	v_exp_f32_e32 v151, v151
	v_add_f32_e32 v204, v144, v146
	v_add_f32_e32 v205, v145, v147
	ds_read_b64_tr_b16 v[48:49], v201 offset:26624
	ds_read_b64_tr_b16 v[50:51], v201 offset:28160
	ds_read_b64_tr_b16 v[52:53], v201 offset:26688
	ds_read_b64_tr_b16 v[54:55], v201 offset:28224
	ds_read_b64_tr_b16 v[56:57], v201 offset:29696
	ds_read_b64_tr_b16 v[58:59], v201 offset:31232
	ds_read_b64_tr_b16 v[60:61], v201 offset:29760
	ds_read_b64_tr_b16 v[62:63], v201 offset:31296
	ds_read_b64_tr_b16 v[64:65], v201 offset:32768
	ds_read_b64_tr_b16 v[66:67], v201 offset:34304
	ds_read_b64_tr_b16 v[68:69], v201 offset:32832
	ds_read_b64_tr_b16 v[70:71], v201 offset:34368
	ds_read_b64_tr_b16 v[72:73], v201 offset:35840
	ds_read_b64_tr_b16 v[74:75], v201 offset:37376
	ds_read_b64_tr_b16 v[76:77], v201 offset:35904
	ds_read_b64_tr_b16 v[78:79], v201 offset:37440
	v_add_f32_e32 v204, v204, v148
	v_add_f32_e32 v205, v205, v149
	v_add_f32_e32 v204, v204, v150
	v_add_f32_e32 v205, v205, v151
	v_cvt_pk_bf16_f32 v144, v144, v145
	v_cvt_pk_bf16_f32 v145, v146, v147
	v_cvt_pk_bf16_f32 v146, v148, v149
	v_cvt_pk_bf16_f32 v147, v150, v151
	v_exp_f32_e32 v152, v152
	v_exp_f32_e32 v153, v153
	s_waitcnt lgkmcnt(14)
	v_mfma_f32_32x32x16_bf16 v[16:31], v[48:51], v[144:147], v[16:31]
	v_exp_f32_e32 v154, v154
	v_exp_f32_e32 v155, v155
	v_exp_f32_e32 v156, v156
	s_waitcnt lgkmcnt(12)
	v_mfma_f32_32x32x16_bf16 v[0:15], v[52:55], v[144:147], v[0:15]
	v_exp_f32_e32 v157, v157
	v_exp_f32_e32 v158, v158
	v_exp_f32_e32 v159, v159
	v_add_f32_e32 v204, v204, v152
	v_add_f32_e32 v205, v205, v153
	v_add_f32_e32 v204, v204, v154
	v_add_f32_e32 v205, v205, v155
	v_add_f32_e32 v204, v204, v156
	v_add_f32_e32 v205, v205, v157
	v_add_f32_e32 v204, v204, v158
	v_add_f32_e32 v205, v205, v159
	v_cvt_pk_bf16_f32 v152, v152, v153
	v_cvt_pk_bf16_f32 v153, v154, v155
	v_cvt_pk_bf16_f32 v154, v156, v157
	v_cvt_pk_bf16_f32 v155, v158, v159
	v_exp_f32_e32 v160, v160
	v_exp_f32_e32 v161, v161
	s_waitcnt lgkmcnt(10)
	v_mfma_f32_32x32x16_bf16 v[16:31], v[56:59], v[152:155], v[16:31]
	v_exp_f32_e32 v162, v162
	v_exp_f32_e32 v163, v163
	v_exp_f32_e32 v164, v164
	s_waitcnt lgkmcnt(8)
	v_mfma_f32_32x32x16_bf16 v[0:15], v[60:63], v[152:155], v[0:15]
	v_exp_f32_e32 v165, v165
	v_exp_f32_e32 v166, v166
	v_exp_f32_e32 v167, v167
	v_add_f32_e32 v204, v204, v160
	v_add_f32_e32 v205, v205, v161
	v_add_f32_e32 v204, v204, v162
	v_add_f32_e32 v205, v205, v163
	v_add_f32_e32 v204, v204, v164
	v_add_f32_e32 v205, v205, v165
	v_add_f32_e32 v204, v204, v166
	v_add_f32_e32 v205, v205, v167
	v_cvt_pk_bf16_f32 v160, v160, v161
	v_cvt_pk_bf16_f32 v161, v162, v163
	v_cvt_pk_bf16_f32 v162, v164, v165
	v_cvt_pk_bf16_f32 v163, v166, v167
	v_exp_f32_e32 v168, v168
	v_exp_f32_e32 v169, v169
	s_waitcnt lgkmcnt(6)
	v_mfma_f32_32x32x16_bf16 v[16:31], v[64:67], v[160:163], v[16:31]
	v_exp_f32_e32 v170, v170
	v_exp_f32_e32 v171, v171
	v_exp_f32_e32 v172, v172
	s_waitcnt lgkmcnt(4)
	v_mfma_f32_32x32x16_bf16 v[0:15], v[68:71], v[160:163], v[0:15]
	v_exp_f32_e32 v173, v173
	v_exp_f32_e32 v174, v174
	v_exp_f32_e32 v175, v175
	v_add_f32_e32 v204, v204, v168
	v_add_f32_e32 v205, v205, v169
	v_add_f32_e32 v204, v204, v170
	v_add_f32_e32 v205, v205, v171
	v_add_f32_e32 v204, v204, v172
	v_add_f32_e32 v205, v205, v173
	v_add_f32_e32 v204, v204, v174
	v_add_f32_e32 v205, v205, v175
	v_cvt_pk_bf16_f32 v168, v168, v169
	v_cvt_pk_bf16_f32 v169, v170, v171
	v_cvt_pk_bf16_f32 v170, v172, v173
	v_cvt_pk_bf16_f32 v171, v174, v175
	s_nop 1
	s_waitcnt lgkmcnt(2)
	v_mfma_f32_32x32x16_bf16 v[16:31], v[72:75], v[168:171], v[16:31]
	s_waitcnt lgkmcnt(0)
	v_mfma_f32_32x32x16_bf16 v[0:15], v[76:79], v[168:171], v[0:15]
	s_waitcnt vmcnt(5)
	ds_write_b128 v198, v[120:123] offset:13312
	s_waitcnt vmcnt(4)
	ds_write_b128 v199, v[124:127] offset:13312
	s_waitcnt vmcnt(3)
	ds_write_b128 v200, v[128:131] offset:38912
	v_add_f32_e32 v204, v204, v205
	v_add_f32_e32 v203, v203, v204
	s_mov_b32 s6, 0x43800000
	s_cmp_eq_u32 s13, 0
	s_cselect_b32 s6, 0xbf800000, s6
	s_cbranch_scc1 .Lm1_rareA
	v_cmp_lt_f32_e32 vcc, 0x43000000, v204
	s_cbranch_vccz .Lm1_noresA

.Lm1_noresA:
	s_waitcnt lgkmcnt(0)
	s_barrier
	ds_read_b128 v[48:51], v184 offset:13312
	ds_read_b128 v[52:55], v184 offset:13344
	ds_read_b128 v[56:59], v184 offset:13376
	ds_read_b128 v[60:63], v184 offset:13408
	ds_read_b128 v[64:67], v184 offset:13440
	ds_read_b128 v[68:71], v184 offset:13472
	ds_read_b128 v[72:75], v184 offset:19968
	ds_read_b128 v[76:79], v184 offset:20000
	ds_read_b128 v[80:83], v184 offset:20032
	ds_read_b128 v[84:87], v184 offset:20064
	ds_read_b128 v[88:91], v184 offset:20096
	ds_read_b128 v[92:95], v184 offset:20128
	s_min_u32 s6, s13, 32
	s_cmp_lt_u32 s13, 29
	s_cselect_b32 s7, 0, 0xffffffe0
	s_cselect_b32 s8, s15, s12
	s_add_i32 s6, s6, s7
	s_lshl_b32 s6, s6, 6
	s_add_i32 s8, s6, s8
	s_addk_i32 s8, 0xc0
	v_add_u32_e32 v208, s8, v194
	v_ashrrev_i32_e32 v209, 31, v208
	s_and_saveexec_b64 s[6:7], s[0:1]
	s_xor_b64 s[6:7], exec, s[6:7]
	v_mad_i64_i32 v[206:207], s[10:11], v208, s33, v[180:181]
	v_lshl_add_u64 v[206:207], v[206:207], 0, s[28:29]
	s_andn2_saveexec_b64 s[6:7], s[6:7]
	v_lshlrev_b64 v[206:207], 9, v[208:209]
	v_lshl_add_u64 v[206:207], v[182:183], 0, v[206:207]
	s_or_b64 exec, exec, s[6:7]
	global_load_dwordx4 v[120:123], v[206:207], off
	v_or_b32_e32 v208, s8, v195
	v_ashrrev_i32_e32 v209, 31, v208
	s_and_saveexec_b64 s[6:7], s[2:3]
	s_xor_b64 s[6:7], exec, s[6:7]
	v_mad_i64_i32 v[206:207], s[10:11], v208, s33, v[190:191]
	v_lshl_add_u64 v[206:207], v[206:207], 0, s[28:29]
	s_andn2_saveexec_b64 s[6:7], s[6:7]
	v_lshlrev_b64 v[206:207], 9, v[208:209]
	v_lshl_add_u64 v[206:207], v[192:193], 0, v[206:207]
	s_or_b64 exec, exec, s[6:7]
	global_load_dwordx4 v[124:127], v[206:207], off
	v_add_u32_e32 v206, s8, v196
	v_ashrrev_i32_e32 v207, 31, v206
	v_lshlrev_b64 v[206:207], 9, v[206:207]
	v_lshl_add_u64 v[206:207], v[178:179], 0, v[206:207]
	global_load_dwordx4 v[128:131], v[206:207], off
	s_waitcnt lgkmcnt(11)
	v_mfma_f32_32x32x16_bf16 v[144:159], v[48:51], v[96:99], v[32:47]
	s_waitcnt lgkmcnt(10)
	v_mfma_f32_32x32x16_bf16 v[144:159], v[52:55], v[100:103], v[144:159]
	s_waitcnt lgkmcnt(9)
	v_mfma_f32_32x32x16_bf16 v[144:159], v[56:59], v[104:107], v[144:159]
	s_waitcnt lgkmcnt(8)
	v_mfma_f32_32x32x16_bf16 v[144:159], v[60:63], v[108:111], v[144:159]
	s_waitcnt lgkmcnt(7)
	v_mfma_f32_32x32x16_bf16 v[144:159], v[64:67], v[112:115], v[144:159]
	s_waitcnt lgkmcnt(6)
	v_mfma_f32_32x32x16_bf16 v[144:159], v[68:71], v[116:119], v[144:159]
	s_waitcnt lgkmcnt(5)
	v_mfma_f32_32x32x16_bf16 v[160:175], v[72:75], v[96:99], v[32:47]
	s_waitcnt lgkmcnt(4)
	v_mfma_f32_32x32x16_bf16 v[160:175], v[76:79], v[100:103], v[160:175]
	s_waitcnt lgkmcnt(3)
	v_mfma_f32_32x32x16_bf16 v[160:175], v[80:83], v[104:107], v[160:175]
	s_nop 5
	s_waitcnt lgkmcnt(2)
	v_mfma_f32_32x32x16_bf16 v[160:175], v[84:87], v[108:111], v[160:175]
	v_exp_f32_e32 v144, v144
	v_exp_f32_e32 v145, v145
	v_exp_f32_e32 v146, v146
	s_waitcnt lgkmcnt(1)
	v_mfma_f32_32x32x16_bf16 v[160:175], v[88:91], v[112:115], v[160:175]
	v_exp_f32_e32 v147, v147
	v_exp_f32_e32 v148, v148
	v_exp_f32_e32 v149, v149
	s_waitcnt lgkmcnt(0)
	v_mfma_f32_32x32x16_bf16 v[160:175], v[92:95], v[116:119], v[160:175]
	v_exp_f32_e32 v150, v150
	v_exp_f32_e32 v151, v151
	v_add_f32_e32 v204, v144, v146
	v_add_f32_e32 v205, v145, v147
	ds_read_b64_tr_b16 v[48:49], v201 offset:38912
	ds_read_b64_tr_b16 v[50:51], v201 offset:40448
	ds_read_b64_tr_b16 v[52:53], v201 offset:38976
	ds_read_b64_tr_b16 v[54:55], v201 offset:40512
	ds_read_b64_tr_b16 v[56:57], v201 offset:41984
	ds_read_b64_tr_b16 v[58:59], v201 offset:43520
	ds_read_b64_tr_b16 v[60:61], v201 offset:42048
	ds_read_b64_tr_b16 v[62:63], v201 offset:43584
	ds_read_b64_tr_b16 v[64:65], v201 offset:45056
	ds_read_b64_tr_b16 v[66:67], v201 offset:46592
	ds_read_b64_tr_b16 v[68:69], v201 offset:45120
	ds_read_b64_tr_b16 v[70:71], v201 offset:46656
	ds_read_b64_tr_b16 v[72:73], v201 offset:48128
	ds_read_b64_tr_b16 v[74:75], v201 offset:49664
	ds_read_b64_tr_b16 v[76:77], v201 offset:48192
	ds_read_b64_tr_b16 v[78:79], v201 offset:49728
	v_add_f32_e32 v204, v204, v148
	v_add_f32_e32 v205, v205, v149
	v_add_f32_e32 v204, v204, v150
	v_add_f32_e32 v205, v205, v151
	v_cvt_pk_bf16_f32 v144, v144, v145
	v_cvt_pk_bf16_f32 v145, v146, v147
	v_cvt_pk_bf16_f32 v146, v148, v149
	v_cvt_pk_bf16_f32 v147, v150, v151
	v_exp_f32_e32 v152, v152
	v_exp_f32_e32 v153, v153
	s_waitcnt lgkmcnt(14)
	v_mfma_f32_32x32x16_bf16 v[16:31], v[48:51], v[144:147], v[16:31]
	v_exp_f32_e32 v154, v154
	v_exp_f32_e32 v155, v155
	v_exp_f32_e32 v156, v156
	s_waitcnt lgkmcnt(12)
	v_mfma_f32_32x32x16_bf16 v[0:15], v[52:55], v[144:147], v[0:15]
	v_exp_f32_e32 v157, v157
	v_exp_f32_e32 v158, v158
	v_exp_f32_e32 v159, v159
	v_add_f32_e32 v204, v204, v152
	v_add_f32_e32 v205, v205, v153
	v_add_f32_e32 v204, v204, v154
	v_add_f32_e32 v205, v205, v155
	v_add_f32_e32 v204, v204, v156
	v_add_f32_e32 v205, v205, v157
	v_add_f32_e32 v204, v204, v158
	v_add_f32_e32 v205, v205, v159
	v_cvt_pk_bf16_f32 v152, v152, v153
	v_cvt_pk_bf16_f32 v153, v154, v155
	v_cvt_pk_bf16_f32 v154, v156, v157
	v_cvt_pk_bf16_f32 v155, v158, v159
	v_exp_f32_e32 v160, v160
	v_exp_f32_e32 v161, v161
	s_waitcnt lgkmcnt(10)
	v_mfma_f32_32x32x16_bf16 v[16:31], v[56:59], v[152:155], v[16:31]
	v_exp_f32_e32 v162, v162
	v_exp_f32_e32 v163, v163
	v_exp_f32_e32 v164, v164
	s_waitcnt lgkmcnt(8)
	v_mfma_f32_32x32x16_bf16 v[0:15], v[60:63], v[152:155], v[0:15]
	v_exp_f32_e32 v165, v165
	v_exp_f32_e32 v166, v166
	v_exp_f32_e32 v167, v167
	v_add_f32_e32 v204, v204, v160
	v_add_f32_e32 v205, v205, v161
	v_add_f32_e32 v204, v204, v162
	v_add_f32_e32 v205, v205, v163
	v_add_f32_e32 v204, v204, v164
	v_add_f32_e32 v205, v205, v165
	v_add_f32_e32 v204, v204, v166
	v_add_f32_e32 v205, v205, v167
	v_cvt_pk_bf16_f32 v160, v160, v161
	v_cvt_pk_bf16_f32 v161, v162, v163
	v_cvt_pk_bf16_f32 v162, v164, v165
	v_cvt_pk_bf16_f32 v163, v166, v167
	v_exp_f32_e32 v168, v168
	v_exp_f32_e32 v169, v169
	s_waitcnt lgkmcnt(6)
	v_mfma_f32_32x32x16_bf16 v[16:31], v[64:67], v[160:163], v[16:31]
	v_exp_f32_e32 v170, v170
	v_exp_f32_e32 v171, v171
	v_exp_f32_e32 v172, v172
	s_waitcnt lgkmcnt(4)
	v_mfma_f32_32x32x16_bf16 v[0:15], v[68:71], v[160:163], v[0:15]
	v_exp_f32_e32 v173, v173
	v_exp_f32_e32 v174, v174
	v_exp_f32_e32 v175, v175
	v_add_f32_e32 v204, v204, v168
	v_add_f32_e32 v205, v205, v169
	v_add_f32_e32 v204, v204, v170
	v_add_f32_e32 v205, v205, v171
	v_add_f32_e32 v204, v204, v172
	v_add_f32_e32 v205, v205, v173
	v_add_f32_e32 v204, v204, v174
	v_add_f32_e32 v205, v205, v175
	v_cvt_pk_bf16_f32 v168, v168, v169
	v_cvt_pk_bf16_f32 v169, v170, v171
	v_cvt_pk_bf16_f32 v170, v172, v173
	v_cvt_pk_bf16_f32 v171, v174, v175
	s_nop 1
	s_waitcnt lgkmcnt(2)
	v_mfma_f32_32x32x16_bf16 v[16:31], v[72:75], v[168:171], v[16:31]
	s_waitcnt lgkmcnt(0)
	v_mfma_f32_32x32x16_bf16 v[0:15], v[76:79], v[168:171], v[0:15]
	s_cmp_gt_u32 s13, 33
	s_cbranch_scc1 .Lm1_skipw
	s_waitcnt vmcnt(5)
	ds_write_b128 v198, v[132:135]
	s_waitcnt vmcnt(4)
	ds_write_b128 v199, v[136:139]
	s_waitcnt vmcnt(3)
	ds_write_b128 v200, v[140:143] offset:26624

.LBB0_903:
	v_readlane_b32 s26, v255, 31
	v_readlane_b32 s27, v255, 32
	ds_read_b32 v65, v177
	ds_read_b32 v64, v177 offset:128
	v_readlane_b32 s26, v255, 35
	v_readlane_b32 s27, v255, 36
	ds_read_b32 v67, v177 offset:4
	ds_read_b32 v66, v177 offset:132
	ds_read_b32 v69, v177 offset:8
	ds_read_b32 v68, v177 offset:136
	ds_read_b32 v71, v177 offset:12
	ds_read_b32 v70, v177 offset:140
	ds_read_b32 v73, v177 offset:32
	ds_read_b32 v72, v177 offset:160
	ds_read_b32 v75, v177 offset:36
	ds_read_b32 v74, v177 offset:164
	ds_read_b32 v77, v177 offset:40
	ds_read_b32 v76, v177 offset:168
	ds_read_b32 v79, v177 offset:44
	ds_read_b32 v78, v177 offset:172
	ds_read_b32 v81, v177 offset:64
	ds_read_b32 v80, v177 offset:192
	ds_read_b32 v83, v177 offset:68
	ds_read_b32 v82, v177 offset:196
	ds_read_b32 v85, v177 offset:72
	ds_read_b32 v84, v177 offset:200
	ds_read_b32 v87, v177 offset:76
	ds_read_b32 v86, v177 offset:204
	ds_read_b32 v89, v177 offset:96
	ds_read_b32 v88, v177 offset:224
	ds_read_b32 v91, v177 offset:100
	ds_read_b32 v90, v177 offset:228
	ds_read_b32 v93, v177 offset:104
	ds_read_b32 v92, v177 offset:232
	ds_read_b32 v95, v177 offset:108
	ds_read_b32 v94, v177 offset:236
	v_readlane_b32 s24, v255, 33
	s_waitcnt lgkmcnt(0)
	v_fmac_f32_e32 v65, 0x3e38aa3b, v48
	v_fmac_f32_e32 v64, 0x3e38aa3b, v32
	v_fmac_f32_e32 v67, 0x3e38aa3b, v49
	v_readlane_b32 s25, v255, 34
	v_fmac_f32_e32 v66, 0x3e38aa3b, v33
	v_cndmask_b32_e64 v48, v65, v238, s[40:41]
	v_cndmask_b32_e64 v32, v238, v64, s[42:43]
	v_cndmask_b32_e64 v49, v67, v238, s[24:25]
	v_cndmask_b32_e64 v33, v238, v66, s[48:49]
	v_max_f32_e32 v64, v48, v32
	v_max_f32_e32 v65, v49, v33
	s_mov_b32 s24, 0xf149f2ca
	v_max3_f32 v64, v64, s24, v65
	v_readlane_b32 s24, v255, 37
	v_fmac_f32_e32 v69, 0x3e38aa3b, v50
	v_readlane_b32 s25, v255, 38
	v_fmac_f32_e32 v68, 0x3e38aa3b, v34
	v_fmac_f32_e32 v71, 0x3e38aa3b, v51
	v_fmac_f32_e32 v70, 0x3e38aa3b, v35
	v_cndmask_b32_e64 v50, v69, v238, s[24:25]
	v_cndmask_b32_e64 v34, v238, v68, s[54:55]
	v_cndmask_b32_e64 v51, v71, v238, s[56:57]
	v_cndmask_b32_e64 v35, v238, v70, s[60:61]
	v_fmac_f32_e32 v73, 0x3e38aa3b, v52
	v_fmac_f32_e32 v72, 0x3e38aa3b, v36
	v_fmac_f32_e32 v75, 0x3e38aa3b, v53
	v_fmac_f32_e32 v74, 0x3e38aa3b, v37
	v_max_f32_e32 v65, v50, v34
	v_max_f32_e32 v66, v51, v35
	v_cndmask_b32_e64 v52, v73, v238, s[62:63]
	v_cndmask_b32_e64 v36, v238, v72, s[66:67]
	v_cndmask_b32_e64 v53, v75, v238, s[68:69]
	v_cndmask_b32_e64 v37, v238, v74, s[72:73]
	v_fmac_f32_e32 v77, 0x3e38aa3b, v54
	v_fmac_f32_e32 v76, 0x3e38aa3b, v38
	v_fmac_f32_e32 v79, 0x3e38aa3b, v55
	v_fmac_f32_e32 v78, 0x3e38aa3b, v39
	v_max3_f32 v64, v64, v65, v66
	v_max_f32_e32 v65, v52, v36
	v_max_f32_e32 v66, v53, v37
	v_cndmask_b32_e64 v54, v77, v238, s[74:75]
	v_cndmask_b32_e64 v38, v238, v76, s[78:79]
	v_cndmask_b32_e64 v55, v79, v238, s[80:81]
	v_cndmask_b32_e64 v39, v238, v78, s[84:85]
	v_fmac_f32_e32 v81, 0x3e38aa3b, v56
	v_fmac_f32_e32 v80, 0x3e38aa3b, v40
	v_fmac_f32_e32 v83, 0x3e38aa3b, v57
	v_fmac_f32_e32 v82, 0x3e38aa3b, v41
	v_max3_f32 v64, v64, v65, v66
	v_max_f32_e32 v65, v54, v38
	v_max_f32_e32 v66, v55, v39
	v_cndmask_b32_e64 v56, v238, v81, s[86:87]
	v_cndmask_b32_e64 v40, v238, v80, s[88:89]
	v_cndmask_b32_e64 v57, v238, v83, s[90:91]
	v_cndmask_b32_e64 v41, v238, v82, s[92:93]
	v_fmac_f32_e32 v85, 0x3e38aa3b, v58
	v_fmac_f32_e32 v84, 0x3e38aa3b, v42
	v_fmac_f32_e32 v87, 0x3e38aa3b, v59
	v_fmac_f32_e32 v86, 0x3e38aa3b, v43
	v_max3_f32 v64, v64, v65, v66
	v_max_f32_e32 v65, v56, v40
	v_max_f32_e32 v66, v57, v41
	v_cndmask_b32_e64 v58, v238, v85, s[94:95]
	v_cndmask_b32_e64 v42, v238, v84, s[96:97]
	v_cndmask_b32_e64 v59, v238, v87, s[0:1]
	v_cndmask_b32_e64 v43, v238, v86, s[2:3]
	v_fmac_f32_e32 v89, 0x3e38aa3b, v60
	v_fmac_f32_e32 v88, 0x3e38aa3b, v44
	v_fmac_f32_e32 v91, 0x3e38aa3b, v61
	v_fmac_f32_e32 v90, 0x3e38aa3b, v45
	v_max3_f32 v64, v64, v65, v66
	v_max_f32_e32 v65, v58, v42
	v_max_f32_e32 v66, v59, v43
	v_cndmask_b32_e64 v60, v238, v89, s[4:5]
	v_cndmask_b32_e64 v44, v238, v88, s[6:7]
	v_cndmask_b32_e64 v61, v238, v91, s[8:9]
	v_cndmask_b32_e64 v45, v238, v90, s[10:11]
	v_fmac_f32_e32 v93, 0x3e38aa3b, v62
	v_fmac_f32_e32 v92, 0x3e38aa3b, v46
	v_fmac_f32_e32 v95, 0x3e38aa3b, v63
	v_fmac_f32_e32 v94, 0x3e38aa3b, v47
	v_max3_f32 v64, v64, v65, v66
	v_max_f32_e32 v65, v60, v44
	v_max_f32_e32 v66, v61, v45
	v_cndmask_b32_e64 v62, v238, v93, s[12:13]
	v_cndmask_b32_e64 v46, v238, v92, s[14:15]
	v_cndmask_b32_e64 v63, v238, v95, s[16:17]
	v_cndmask_b32_e64 v47, v238, v94, s[18:19]
	v_max3_f32 v64, v64, v65, v66
	v_max_f32_e32 v65, v62, v46
	v_max_f32_e32 v66, v63, v47
	v_max3_f32 v64, v64, v65, v66
	v_mov_b32_e32 v65, v64
	s_nop 1
	v_permlane32_swap_b32_e32 v64, v65
	v_max_f32_e32 v65, v65, v65
	v_max_f32_e32 v64, v64, v64
	v_max_f32_e32 v64, v64, v65
	v_cmp_gt_f32_e32 vcc, v64, v179
	s_cmp_eq_u64 vcc, 0
	v_max_f32_e32 v64, v178, v64
	s_cselect_b64 vcc, -1, 0
	v_cndmask_b32_e32 v170, v64, v168, vcc
	v_sub_f32_e32 v32, v32, v170
	v_exp_f32_e32 v80, v32
	v_sub_f32_e32 v32, v49, v170
	v_exp_f32_e32 v65, v32
	v_sub_f32_e32 v32, v33, v170
	v_exp_f32_e32 v81, v32
	v_sub_f32_e32 v32, v50, v170
	v_exp_f32_e32 v66, v32
	v_sub_f32_e32 v32, v34, v170
	v_exp_f32_e32 v82, v32
	v_sub_f32_e32 v32, v51, v170
	v_exp_f32_e32 v67, v32
	v_sub_f32_e32 v32, v35, v170
	v_exp_f32_e32 v83, v32
	v_sub_f32_e32 v32, v52, v170
	v_exp_f32_e32 v68, v32
	v_sub_f32_e32 v32, v36, v170
	v_exp_f32_e32 v84, v32
	v_sub_f32_e32 v32, v53, v170
	v_exp_f32_e32 v69, v32
	v_sub_f32_e32 v32, v37, v170
	v_exp_f32_e32 v85, v32
	v_sub_f32_e32 v32, v54, v170
	v_exp_f32_e32 v70, v32
	v_sub_f32_e32 v32, v38, v170
	v_exp_f32_e32 v86, v32
	v_sub_f32_e32 v32, v55, v170
	v_exp_f32_e32 v71, v32
	v_sub_f32_e32 v32, v39, v170
	v_exp_f32_e32 v87, v32
	v_sub_f32_e32 v32, v56, v170
	v_exp_f32_e32 v72, v32
	v_sub_f32_e32 v32, v40, v170
	v_exp_f32_e32 v88, v32
	v_sub_f32_e32 v32, v57, v170
	v_exp_f32_e32 v73, v32
	v_sub_f32_e32 v32, v41, v170
	v_exp_f32_e32 v89, v32
	v_sub_f32_e32 v32, v58, v170
	v_exp_f32_e32 v74, v32
	v_sub_f32_e32 v32, v42, v170
	v_exp_f32_e32 v90, v32
	v_sub_f32_e32 v32, v59, v170
	v_exp_f32_e32 v75, v32
	v_sub_f32_e32 v32, v43, v170
	v_exp_f32_e32 v91, v32
	v_sub_f32_e32 v32, v60, v170
	v_exp_f32_e32 v76, v32
	v_sub_f32_e32 v32, v44, v170
	v_exp_f32_e32 v92, v32
	v_sub_f32_e32 v32, v61, v170
	v_exp_f32_e32 v77, v32
	v_sub_f32_e32 v32, v45, v170
	v_exp_f32_e32 v93, v32
	v_sub_f32_e32 v32, v62, v170
	v_exp_f32_e32 v78, v32
	v_sub_f32_e32 v32, v46, v170
	v_sub_f32_e32 v48, v48, v170
	v_exp_f32_e32 v94, v32
	v_sub_f32_e32 v32, v63, v170
	v_exp_f32_e32 v64, v48
	v_exp_f32_e32 v79, v32
	v_sub_f32_e32 v95, v47, v170
	v_cmp_gt_f32_e32 vcc, v170, v168
	s_cbranch_vccnz .LBB0_884
	s_branch .LBB0_885

.LBB0_969:
	v_readlane_b32 s26, v255, 31
	v_readlane_b32 s27, v255, 32
	ds_read_b32 v65, v177 offset:124
	ds_read_b32 v64, v177 offset:252
	v_readlane_b32 s26, v255, 35
	v_readlane_b32 s27, v255, 36
	ds_read_b32 v67, v177 offset:128
	ds_read_b32 v66, v177 offset:256
	ds_read_b32 v69, v177 offset:132
	ds_read_b32 v68, v177 offset:260
	ds_read_b32 v71, v177 offset:136
	ds_read_b32 v70, v177 offset:264
	ds_read_b32 v73, v177 offset:156
	ds_read_b32 v72, v177 offset:284
	ds_read_b32 v75, v177 offset:160
	ds_read_b32 v74, v177 offset:288
	ds_read_b32 v77, v177 offset:164
	ds_read_b32 v76, v177 offset:292
	ds_read_b32 v79, v177 offset:168
	ds_read_b32 v78, v177 offset:296
	ds_read_b32 v81, v177 offset:188
	ds_read_b32 v80, v177 offset:316
	ds_read_b32 v83, v177 offset:192
	ds_read_b32 v82, v177 offset:320
	ds_read_b32 v85, v177 offset:196
	ds_read_b32 v84, v177 offset:324
	ds_read_b32 v87, v177 offset:200
	ds_read_b32 v86, v177 offset:328
	ds_read_b32 v89, v177 offset:220
	ds_read_b32 v88, v177 offset:348
	ds_read_b32 v91, v177 offset:224
	ds_read_b32 v90, v177 offset:352
	ds_read_b32 v93, v177 offset:228
	ds_read_b32 v92, v177 offset:356
	ds_read_b32 v95, v177 offset:232
	ds_read_b32 v94, v177 offset:360
	v_readlane_b32 s24, v255, 33
	s_waitcnt lgkmcnt(0)
	v_fmac_f32_e32 v65, 0x3e38aa3b, v48
	v_fmac_f32_e32 v64, 0x3e38aa3b, v32
	v_fmac_f32_e32 v67, 0x3e38aa3b, v49
	v_readlane_b32 s25, v255, 34
	v_fmac_f32_e32 v66, 0x3e38aa3b, v33
	v_cndmask_b32_e64 v48, v65, v238, s[40:41]
	v_cndmask_b32_e64 v32, v238, v64, s[42:43]
	v_cndmask_b32_e64 v49, v67, v238, s[24:25]
	v_cndmask_b32_e64 v33, v238, v66, s[48:49]
	v_max_f32_e32 v64, v48, v32
	v_max_f32_e32 v65, v49, v33
	s_mov_b32 s24, 0xf149f2ca
	v_max3_f32 v64, v64, s24, v65
	v_readlane_b32 s24, v255, 37
	v_fmac_f32_e32 v69, 0x3e38aa3b, v50
	v_readlane_b32 s25, v255, 38
	v_fmac_f32_e32 v68, 0x3e38aa3b, v34
	v_fmac_f32_e32 v71, 0x3e38aa3b, v51
	v_fmac_f32_e32 v70, 0x3e38aa3b, v35
	v_cndmask_b32_e64 v50, v69, v238, s[24:25]
	v_cndmask_b32_e64 v34, v238, v68, s[54:55]
	v_cndmask_b32_e64 v51, v71, v238, s[56:57]
	v_cndmask_b32_e64 v35, v238, v70, s[60:61]
	v_fmac_f32_e32 v73, 0x3e38aa3b, v52
	v_fmac_f32_e32 v72, 0x3e38aa3b, v36
	v_fmac_f32_e32 v75, 0x3e38aa3b, v53
	v_fmac_f32_e32 v74, 0x3e38aa3b, v37
	v_max_f32_e32 v65, v50, v34
	v_max_f32_e32 v66, v51, v35
	v_cndmask_b32_e64 v52, v73, v238, s[62:63]
	v_cndmask_b32_e64 v36, v238, v72, s[66:67]
	v_cndmask_b32_e64 v53, v75, v238, s[68:69]
	v_cndmask_b32_e64 v37, v238, v74, s[72:73]
	v_fmac_f32_e32 v77, 0x3e38aa3b, v54
	v_fmac_f32_e32 v76, 0x3e38aa3b, v38
	v_fmac_f32_e32 v79, 0x3e38aa3b, v55
	v_fmac_f32_e32 v78, 0x3e38aa3b, v39
	v_max3_f32 v64, v64, v65, v66
	v_max_f32_e32 v65, v52, v36
	v_max_f32_e32 v66, v53, v37
	v_cndmask_b32_e64 v54, v77, v238, s[74:75]
	v_cndmask_b32_e64 v38, v238, v76, s[78:79]
	v_cndmask_b32_e64 v55, v79, v238, s[80:81]
	v_cndmask_b32_e64 v39, v238, v78, s[84:85]
	v_fmac_f32_e32 v81, 0x3e38aa3b, v56
	v_fmac_f32_e32 v80, 0x3e38aa3b, v40
	v_fmac_f32_e32 v83, 0x3e38aa3b, v57
	v_fmac_f32_e32 v82, 0x3e38aa3b, v41
	v_max3_f32 v64, v64, v65, v66
	v_max_f32_e32 v65, v54, v38
	v_max_f32_e32 v66, v55, v39
	v_cndmask_b32_e64 v56, v238, v81, s[86:87]
	v_cndmask_b32_e64 v40, v238, v80, s[88:89]
	v_cndmask_b32_e64 v57, v238, v83, s[90:91]
	v_cndmask_b32_e64 v41, v238, v82, s[92:93]
	v_fmac_f32_e32 v85, 0x3e38aa3b, v58
	v_fmac_f32_e32 v84, 0x3e38aa3b, v42
	v_fmac_f32_e32 v87, 0x3e38aa3b, v59
	v_fmac_f32_e32 v86, 0x3e38aa3b, v43
	v_max3_f32 v64, v64, v65, v66
	v_max_f32_e32 v65, v56, v40
	v_max_f32_e32 v66, v57, v41
	v_cndmask_b32_e64 v58, v238, v85, s[94:95]
	v_cndmask_b32_e64 v42, v238, v84, s[96:97]
	v_cndmask_b32_e64 v59, v238, v87, s[0:1]
	v_cndmask_b32_e64 v43, v238, v86, s[2:3]
	v_fmac_f32_e32 v89, 0x3e38aa3b, v60
	v_fmac_f32_e32 v88, 0x3e38aa3b, v44
	v_fmac_f32_e32 v91, 0x3e38aa3b, v61
	v_fmac_f32_e32 v90, 0x3e38aa3b, v45
	v_max3_f32 v64, v64, v65, v66
	v_max_f32_e32 v65, v58, v42
	v_max_f32_e32 v66, v59, v43
	v_cndmask_b32_e64 v60, v238, v89, s[4:5]
	v_cndmask_b32_e64 v44, v238, v88, s[6:7]
	v_cndmask_b32_e64 v61, v238, v91, s[8:9]
	v_cndmask_b32_e64 v45, v238, v90, s[10:11]
	v_fmac_f32_e32 v93, 0x3e38aa3b, v62
	v_fmac_f32_e32 v92, 0x3e38aa3b, v46
	v_fmac_f32_e32 v95, 0x3e38aa3b, v63
	v_fmac_f32_e32 v94, 0x3e38aa3b, v47
	v_max3_f32 v64, v64, v65, v66
	v_max_f32_e32 v65, v60, v44
	v_max_f32_e32 v66, v61, v45
	v_cndmask_b32_e64 v62, v238, v93, s[12:13]
	v_cndmask_b32_e64 v46, v238, v92, s[14:15]
	v_cndmask_b32_e64 v63, v238, v95, s[16:17]
	v_cndmask_b32_e64 v47, v238, v94, s[18:19]
	v_max3_f32 v64, v64, v65, v66
	v_max_f32_e32 v65, v62, v46
	v_max_f32_e32 v66, v63, v47
	v_max3_f32 v64, v64, v65, v66
	v_mov_b32_e32 v65, v64
	s_nop 1
	v_permlane32_swap_b32_e32 v64, v65
	v_max_f32_e32 v65, v65, v65
	v_max_f32_e32 v64, v64, v64
	v_max_f32_e32 v64, v64, v65
	v_cmp_gt_f32_e32 vcc, v64, v179
	s_cmp_eq_u64 vcc, 0
	v_max_f32_e32 v64, v178, v64
	s_cselect_b64 vcc, -1, 0
	v_cndmask_b32_e32 v168, v64, v170, vcc
	v_sub_f32_e32 v32, v32, v168
	v_exp_f32_e32 v80, v32
	v_sub_f32_e32 v32, v49, v168
	v_exp_f32_e32 v65, v32
	v_sub_f32_e32 v32, v33, v168
	v_exp_f32_e32 v81, v32
	v_sub_f32_e32 v32, v50, v168
	v_exp_f32_e32 v66, v32
	v_sub_f32_e32 v32, v34, v168
	v_exp_f32_e32 v82, v32
	v_sub_f32_e32 v32, v51, v168
	v_exp_f32_e32 v67, v32
	v_sub_f32_e32 v32, v35, v168
	v_exp_f32_e32 v83, v32
	v_sub_f32_e32 v32, v52, v168
	v_exp_f32_e32 v68, v32
	v_sub_f32_e32 v32, v36, v168
	v_exp_f32_e32 v84, v32
	v_sub_f32_e32 v32, v53, v168
	v_exp_f32_e32 v69, v32
	v_sub_f32_e32 v32, v37, v168
	v_exp_f32_e32 v85, v32
	v_sub_f32_e32 v32, v54, v168
	v_exp_f32_e32 v70, v32
	v_sub_f32_e32 v32, v38, v168
	v_exp_f32_e32 v86, v32
	v_sub_f32_e32 v32, v55, v168
	v_exp_f32_e32 v71, v32
	v_sub_f32_e32 v32, v39, v168
	v_exp_f32_e32 v87, v32
	v_sub_f32_e32 v32, v56, v168
	v_exp_f32_e32 v72, v32
	v_sub_f32_e32 v32, v40, v168
	v_exp_f32_e32 v88, v32
	v_sub_f32_e32 v32, v57, v168
	v_exp_f32_e32 v73, v32
	v_sub_f32_e32 v32, v41, v168
	v_exp_f32_e32 v89, v32
	v_sub_f32_e32 v32, v58, v168
	v_exp_f32_e32 v74, v32
	v_sub_f32_e32 v32, v42, v168
	v_exp_f32_e32 v90, v32
	v_sub_f32_e32 v32, v59, v168
	v_exp_f32_e32 v75, v32
	v_sub_f32_e32 v32, v43, v168
	v_exp_f32_e32 v91, v32
	v_sub_f32_e32 v32, v60, v168
	v_exp_f32_e32 v76, v32
	v_sub_f32_e32 v32, v44, v168
	v_exp_f32_e32 v92, v32
	v_sub_f32_e32 v32, v61, v168
	v_exp_f32_e32 v77, v32
	v_sub_f32_e32 v32, v45, v168
	v_exp_f32_e32 v93, v32
	v_sub_f32_e32 v32, v62, v168
	v_exp_f32_e32 v78, v32
	v_sub_f32_e32 v32, v46, v168
	v_sub_f32_e32 v48, v48, v168
	v_exp_f32_e32 v94, v32
	v_sub_f32_e32 v32, v63, v168
	v_exp_f32_e32 v64, v48
	v_exp_f32_e32 v79, v32
	v_sub_f32_e32 v95, v47, v168
	v_cmp_gt_f32_e32 vcc, v168, v170
	s_cbranch_vccnz .LBB0_896
	s_branch .LBB0_897
